# MALL warm-up: each wave touches its 22.5 KB slice of this layer's gate_up weights at gate_up phase entry (3 global_load_dword per wave), on top of LUT batching
# baseline (speedup 1.0000x reference)
.LBB0_652:
	s_waitcnt lgkmcnt(0)
	v_readlane_b32 s4, v255, 20
	s_or_b32 s2, s4, 6
	s_cmp_le_i32 s68, s2
	s_cselect_b64 s[0:1], -1, 0
	s_cmp_lt_i32 s2, s69
	s_cselect_b64 s[2:3], -1, 0
	s_and_b64 s[0:1], s[0:1], s[2:3]
	s_or_b32 s28, s4, 7
	s_cmp_lt_i32 s28, s69
	s_cselect_b64 s[4:5], -1, 0
	s_andn2_b64 vcc, exec, s[0:1]
	s_cbranch_vccnz .LBB0_747
	v_readlane_b32 s0, v253, 0
	v_readlane_b32 s1, v253, 1
	s_load_dwordx2 s[0:1], s[0:1], 0x90
	v_mov_b32_e32 v1, v232
	v_mov_b32_e32 v2, v232
	v_mov_b32_e32 v3, v0
	v_and_b32_e32 v4, 1, v2
	v_ashrrev_i32_e32 v1, 1, v2
	v_lshlrev_b32_e32 v2, 6, v4
	s_waitcnt lgkmcnt(0)
	v_readlane_b32 s98, v255, 20
	v_readfirstlane_b32 s99, v232
	s_sub_i32 s98, s98, 1
	s_lshr_b32 s98, s98, 3
	s_mul_i32 s98, s98, 0x2c00000
	s_add_u32 s98, s98, 0x6900000
	s_lshr_b32 s99, s99, 6
	s_lshl_b32 s100, s77, 3
	s_add_i32 s99, s99, s100
	s_mul_i32 s99, s99, 0x5800
	s_add_u32 s98, s98, s99
	s_add_u32 s100, s0, s98
	s_addc_u32 s101, s1, 0
	v_and_b32_e32 v58, 63, v232
	v_lshlrev_b32_e32 v58, 7, v58
	v_add_u32_e32 v61, 0x2000, v58
	v_add_u32_e32 v62, 0x3800, v58
	global_load_dword v59, v58, s[100:101]
	global_load_dword v60, v61, s[100:101]
	global_load_dword v63, v62, s[100:101]
	s_nop 0
	s_nop 0
	s_nop 0
	v_lshl_add_u64 v[2:3], s[0:1], 0, v[2:3]
	s_mov_b64 s[2:3], 0x34e00000
	v_cmp_lt_i32_e32 vcc, v237, v238
	v_lshl_add_u64 v[50:51], v[2:3], 0, s[2:3]
	v_readlane_b32 s3, v254, 51
	v_cndmask_b32_e32 v2, v236, v237, vcc
	s_mov_b32 s2, 0
	v_lshlrev_b32_e32 v52, 2, v2
	v_cmp_eq_u32_e64 s[38:39], 0, v4
	v_lshl_add_u32 v53, v1, 2, s3
	s_mov_b64 s[6:7], -1
	s_branch .LBB0_655

	.amdhsa_kernel _Z3fwd4Args
		.amdhsa_group_segment_fixed_size 0
		.amdhsa_private_segment_fixed_size 0
		.amdhsa_kernarg_size 416
		.amdhsa_user_sgpr_count 2
		.amdhsa_user_sgpr_dispatch_ptr 0
		.amdhsa_user_sgpr_queue_ptr 0
		.amdhsa_user_sgpr_kernarg_segment_ptr 1
		.amdhsa_user_sgpr_dispatch_id 0
		.amdhsa_user_sgpr_kernarg_preload_length 0
		.amdhsa_user_sgpr_kernarg_preload_offset 0
		.amdhsa_user_sgpr_private_segment_size 0
		.amdhsa_uses_dynamic_stack 0
		.amdhsa_enable_private_segment 0
		.amdhsa_system_sgpr_workgroup_id_x 1
		.amdhsa_system_sgpr_workgroup_id_y 0
		.amdhsa_system_sgpr_workgroup_id_z 0
		.amdhsa_system_sgpr_workgroup_info 0
		.amdhsa_system_vgpr_workitem_id 2
		.amdhsa_next_free_vgpr 256
		.amdhsa_next_free_sgpr 102
		.amdhsa_accum_offset 256
		.amdhsa_reserve_vcc 1
		.amdhsa_float_round_mode_32 0
		.amdhsa_float_round_mode_16_64 0
		.amdhsa_float_denorm_mode_32 3
		.amdhsa_float_denorm_mode_16_64 3
		.amdhsa_dx10_clamp 1
		.amdhsa_ieee_mode 1
		.amdhsa_fp16_overflow 0
		.amdhsa_tg_split 0
		.amdhsa_exception_fp_ieee_invalid_op 0
		.amdhsa_exception_fp_denorm_src 0
		.amdhsa_exception_fp_ieee_div_zero 0
		.amdhsa_exception_fp_ieee_overflow 0
		.amdhsa_exception_fp_ieee_underflow 0
		.amdhsa_exception_fp_ieee_inexact 0
		.amdhsa_exception_int_div_zero 0
	.end_amdhsa_kernel

amdhsa.kernels:
  - .agpr_count:     0
    .args:
      - .offset:         0
        .size:           160
        .value_kind:     by_value
      - .offset:         160
        .size:           4
        .value_kind:     hidden_block_count_x
      - .offset:         164
        .size:           4
        .value_kind:     hidden_block_count_y
      - .offset:         168
        .size:           4
        .value_kind:     hidden_block_count_z
      - .offset:         172
        .size:           2
        .value_kind:     hidden_group_size_x
      - .offset:         174
        .size:           2
        .value_kind:     hidden_group_size_y
      - .offset:         176
        .size:           2
        .value_kind:     hidden_group_size_z
      - .offset:         178
        .size:           2
        .value_kind:     hidden_remainder_x
      - .offset:         180
        .size:           2
        .value_kind:     hidden_remainder_y
      - .offset:         182
        .size:           2
        .value_kind:     hidden_remainder_z
      - .offset:         200
        .size:           8
        .value_kind:     hidden_global_offset_x
      - .offset:         208
        .size:           8
        .value_kind:     hidden_global_offset_y
      - .offset:         216
        .size:           8
        .value_kind:     hidden_global_offset_z
      - .offset:         224
        .size:           2
        .value_kind:     hidden_grid_dims
      - .offset:         248
        .size:           8
        .value_kind:     hidden_multigrid_sync_arg
      - .offset:         280
        .size:           4
        .value_kind:     hidden_dynamic_lds_size
    .group_segment_fixed_size: 0
    .kernarg_segment_align: 8
    .kernarg_segment_size: 416
    .language:       OpenCL C
    .language_version:
      - 2
      - 0
    .max_flat_workgroup_size: 512
    .name:           _Z3fwd4Args
    .private_segment_fixed_size: 0
    .sgpr_count:     108
    .sgpr_spill_count: 199
    .symbol:         _Z3fwd4Args.kd
    .uniform_work_group_size: 1
    .uses_dynamic_stack: false
    .vgpr_count:     256
    .vgpr_spill_count: 0
    .wavefront_size: 64
